# hand-written post pass (16 lanes x 4 cols per head) + rpass mode 0 rewritten with prefetch
# speedup vs baseline: 1.0691x; 1.0103x over previous
.LBB0_213:
	s_or_b64 exec, exec, s[0:1]
	v_readlane_b32 s2, v242, 42
	s_waitcnt lgkmcnt(0)
	v_mov_b32_e32 v0, v137
	v_readlane_b32 s3, v242, 43
	s_barrier
	s_load_dword s0, s[2:3], 0x10
	s_load_dword s45, s[2:3], 0x0
	v_ashrrev_i32_e32 v2, 6, v0
	s_waitcnt lgkmcnt(0)
	s_lshr_b32 s0, s0, 16
	s_cmp_lg_u32 s0, 0
	s_cselect_b64 s[0:1], -1, 0
	s_cmp_lg_u64 s[0:1], 0
	s_addc_u32 s50, s45, 0
	s_lshl_b32 s51, s50, 2
	s_abs_i32 s0, s51
	v_cvt_f32_u32_e32 v1, s0
	s_sub_i32 s3, 0, s0
	s_add_i32 s1, s51, 0x27ff
	s_xor_b32 s2, s1, s51
	v_rcp_iflag_f32_e32 v1, v1
	s_abs_i32 s1, s1
	s_ashr_i32 s2, s2, 31
	v_mul_f32_e32 v1, 0x4f7ffffe, v1
	v_cvt_u32_f32_e32 v1, v1
	s_nop 0
	v_readfirstlane_b32 s4, v1
	s_mul_i32 s3, s3, s4
	s_mul_hi_u32 s3, s4, s3
	s_add_i32 s4, s4, s3
	s_mul_hi_u32 s3, s1, s4
	s_mul_i32 s4, s3, s0
	s_sub_i32 s1, s1, s4
	s_add_i32 s5, s3, 1
	s_sub_i32 s4, s1, s0
	s_cmp_ge_u32 s1, s0
	s_cselect_b32 s3, s5, s3
	s_cselect_b32 s1, s4, s1
	s_add_i32 s4, s3, 1
	s_cmp_ge_u32 s1, s0
	s_cselect_b32 s0, s4, s3
	s_xor_b32 s0, s0, s2
	s_sub_i32 s1, s0, s2
	v_readlane_b32 s0, v242, 0
	v_writelane_b32 v241, s1, 12
	s_nop 0
	v_lshl_add_u32 v1, s0, 2, v2
	v_mul_lo_u32 v16, v1, s1
	v_add_u32_e32 v1, s1, v16
	v_min_i32_e32 v40, 0x2800, v1
	v_cmp_lt_i32_e32 vcc, v16, v40
	s_and_saveexec_b64 s[0:1], vcc
	s_cbranch_execz .LBB0_218
	v_readfirstlane_b32 s6, v16
	v_readfirstlane_b32 s7, v40
	v_readlane_b32 s36, v242, 42
	v_readlane_b32 s37, v242, 43
	v_readlane_b32 s14, v242, 1
	v_readlane_b32 s15, v242, 2
	v_readlane_b32 s20, v242, 3
	v_readlane_b32 s21, v242, 4
	v_and_b32_e32 v236, 63, v137
	v_lshlrev_b32_e32 v237, 3, v236
	v_lshlrev_b32_e32 v236, 4, v236
	v_mov_b32_e32 v238, 0x358637bd
	s_sub_u32 s36, s36, 0x118
	s_subb_u32 s37, s37, 0
	s_load_dwordx2 s[12:13], s[36:37], 0x58
	s_load_dwordx4 s[16:19], s[36:37], 0x0
	s_add_u32 s22, s20, 0x2f90000
	s_addc_u32 s23, s21, 0
	s_mov_b32 s8, -1
	s_waitcnt lgkmcnt(0)
	s_cmp_lt_u32 s6, 0x2000
	s_cselect_b32 s24, s16, s18
	s_cselect_b32 s25, s17, s19
	s_cselect_b32 s9, 0, 0x2000
	s_sub_u32 s9, s6, s9
	s_lshl_b32 s9, s9, 12
	s_add_u32 s24, s24, s9
	s_addc_u32 s25, s25, 0
	global_load_dwordx4 v[188:191], v236, s[24:25] offset:0
	global_load_dwordx4 v[192:195], v236, s[24:25] offset:1024
	global_load_dwordx4 v[196:199], v236, s[24:25] offset:2048
	global_load_dwordx4 v[200:203], v236, s[24:25] offset:3072
.Lrp00_loop:
	s_sub_u32 s9, s6, 0x2000
	s_ashr_i32 s9, s9, 10
	s_add_i32 s9, s9, 1
	s_max_i32 s9, s9, 0
	s_cmp_eq_u32 s9, s8
	s_cbranch_scc1 .Lrp00_same0
	s_mov_b32 s8, s9
	s_add_i32 s9, s8, 0
	s_mul_i32 s9, s9, 0x6000
	s_add_u32 s36, s22, s9
	s_addc_u32 s37, s23, 0
	global_load_dwordx4 v[68:71], v236, s[12:13] offset:0
	global_load_dwordx4 v[72:75], v236, s[12:13] offset:1024
	global_load_dwordx4 v[76:79], v236, s[12:13] offset:2048
	global_load_dwordx4 v[100:103], v236, s[12:13] offset:3072
	s_add_u32 s38, s36, 0x1000
	s_addc_u32 s39, s37, 0
	global_load_dwordx4 v[104:107], v236, s[38:39] offset:0
	global_load_dwordx4 v[108:111], v236, s[38:39] offset:1024
	global_load_dwordx4 v[112:115], v236, s[38:39] offset:2048
	global_load_dwordx4 v[116:119], v236, s[38:39] offset:3072
	s_add_u32 s38, s36, 0x0
	s_addc_u32 s39, s37, 0
	global_load_dwordx4 v[172:175], v236, s[38:39] offset:0
	global_load_dwordx4 v[176:179], v236, s[38:39] offset:1024
	global_load_dwordx4 v[180:183], v236, s[38:39] offset:2048
	global_load_dwordx4 v[184:187], v236, s[38:39] offset:3072
	s_waitcnt vmcnt(0)
	v_add_f32_e32 v104, 1.0, v104
	v_add_f32_e32 v105, 1.0, v105
	v_add_f32_e32 v106, 1.0, v106
	v_add_f32_e32 v107, 1.0, v107
	v_add_f32_e32 v108, 1.0, v108
	v_add_f32_e32 v109, 1.0, v109
	v_add_f32_e32 v110, 1.0, v110
	v_add_f32_e32 v111, 1.0, v111
	v_add_f32_e32 v112, 1.0, v112
	v_add_f32_e32 v113, 1.0, v113
	v_add_f32_e32 v114, 1.0, v114
	v_add_f32_e32 v115, 1.0, v115
	v_add_f32_e32 v116, 1.0, v116
	v_add_f32_e32 v117, 1.0, v117
	v_add_f32_e32 v118, 1.0, v118
	v_add_f32_e32 v119, 1.0, v119
	v_mul_f32_e32 v156, v68, v104
	v_mul_f32_e32 v157, v69, v105
	v_mul_f32_e32 v158, v70, v106
	v_mul_f32_e32 v159, v71, v107
	v_mul_f32_e32 v160, v72, v108
	v_mul_f32_e32 v161, v73, v109
	v_mul_f32_e32 v162, v74, v110
	v_mul_f32_e32 v163, v75, v111
	v_mul_f32_e32 v164, v76, v112
	v_mul_f32_e32 v165, v77, v113
	v_mul_f32_e32 v166, v78, v114
	v_mul_f32_e32 v167, v79, v115
	v_mul_f32_e32 v168, v100, v116
	v_mul_f32_e32 v169, v101, v117
	v_mul_f32_e32 v170, v102, v118
	v_mul_f32_e32 v171, v103, v119
.Lrp00_same0:
	s_lshl_b32 s9, s6, 11
	s_add_u32 s9, s9, 0x30f8100
	s_add_u32 s34, s20, s9
	s_addc_u32 s35, s21, 0
	s_add_i32 s6, s6, 1
	s_cmp_lt_u32 s6, s7
	s_cbranch_scc0 .Lrp00_last0
	s_cmp_lt_u32 s6, 0x2000
	s_cselect_b32 s28, s16, s18
	s_cselect_b32 s29, s17, s19
	s_cselect_b32 s9, 0, 0x2000
	s_sub_u32 s9, s6, s9
	s_lshl_b32 s9, s9, 12
	s_add_u32 s28, s28, s9
	s_addc_u32 s29, s29, 0
	global_load_dwordx4 v[212:215], v236, s[28:29] offset:0
	global_load_dwordx4 v[216:219], v236, s[28:29] offset:1024
	global_load_dwordx4 v[220:223], v236, s[28:29] offset:2048
	global_load_dwordx4 v[224:227], v236, s[28:29] offset:3072
	s_waitcnt vmcnt(8)
	s_branch .Lrp00_go0

.Lrp00_go0:
	v_mul_f32_e32 v132, v188, v188
	v_mul_f32_e32 v133, v189, v189
	v_fmac_f32_e32 v132, v190, v190
	v_fmac_f32_e32 v133, v191, v191
	v_fmac_f32_e32 v132, v192, v192
	v_fmac_f32_e32 v133, v193, v193
	v_fmac_f32_e32 v132, v194, v194
	v_fmac_f32_e32 v133, v195, v195
	v_fmac_f32_e32 v132, v196, v196
	v_fmac_f32_e32 v133, v197, v197
	v_fmac_f32_e32 v132, v198, v198
	v_fmac_f32_e32 v133, v199, v199
	v_fmac_f32_e32 v132, v200, v200
	v_fmac_f32_e32 v133, v201, v201
	v_fmac_f32_e32 v132, v202, v202
	v_fmac_f32_e32 v133, v203, v203
	v_add_f32_e32 v132, v132, v133
	s_nop 1
	v_add_f32_dpp v132, v132, v132 quad_perm:[1,0,3,2] row_mask:0xf bank_mask:0xf bound_ctrl:1
	s_nop 1
	v_add_f32_dpp v132, v132, v132 quad_perm:[2,3,0,1] row_mask:0xf bank_mask:0xf bound_ctrl:1
	s_nop 1
	v_add_f32_dpp v132, v132, v132 row_ror:4 row_mask:0xf bank_mask:0xf bound_ctrl:1
	s_nop 1
	v_add_f32_dpp v132, v132, v132 row_ror:8 row_mask:0xf bank_mask:0xf bound_ctrl:1
	s_nop 1
	v_readlane_b32 s9, v132, 0
	v_readlane_b32 s38, v132, 16
	v_readlane_b32 s39, v132, 32
	v_readlane_b32 s40, v132, 48
	s_nop 2
	v_mov_b32_e32 v132, s9
	v_add_f32_e32 v132, s38, v132
	v_mov_b32_e32 v135, s39
	v_add_f32_e32 v135, s40, v135
	v_add_f32_e32 v132, v132, v135
	v_fmamk_f32 v132, v132, 0x3a800000, v238
	v_rsq_f32_e32 v132, v132
	s_nop 0
	v_mul_f32_e32 v116, v188, v132
	v_mul_f32_e32 v117, v189, v132
	v_mul_f32_e32 v118, v190, v132
	v_mul_f32_e32 v119, v191, v132
	v_mul_f32_e32 v120, v192, v132
	v_mul_f32_e32 v121, v193, v132
	v_mul_f32_e32 v122, v194, v132
	v_mul_f32_e32 v123, v195, v132
	v_mul_f32_e32 v124, v196, v132
	v_mul_f32_e32 v125, v197, v132
	v_mul_f32_e32 v126, v198, v132
	v_mul_f32_e32 v127, v199, v132
	v_mul_f32_e32 v128, v200, v132
	v_mul_f32_e32 v129, v201, v132
	v_mul_f32_e32 v130, v202, v132
	v_mul_f32_e32 v131, v203, v132
	v_fma_f32 v116, v116, v156, v172
	v_fma_f32 v117, v117, v157, v173
	v_fma_f32 v118, v118, v158, v174
	v_fma_f32 v119, v119, v159, v175
	v_fma_f32 v120, v120, v160, v176
	v_fma_f32 v121, v121, v161, v177
	v_fma_f32 v122, v122, v162, v178
	v_fma_f32 v123, v123, v163, v179
	v_fma_f32 v124, v124, v164, v180
	v_fma_f32 v125, v125, v165, v181
	v_fma_f32 v126, v126, v166, v182
	v_fma_f32 v127, v127, v167, v183
	v_fma_f32 v128, v128, v168, v184
	v_fma_f32 v129, v129, v169, v185
	v_fma_f32 v130, v130, v170, v186
	v_fma_f32 v131, v131, v171, v187
	v_cvt_pk_bf16_f32 v116, v116, v117
	v_cvt_pk_bf16_f32 v117, v118, v119
	v_cvt_pk_bf16_f32 v118, v120, v121
	v_cvt_pk_bf16_f32 v119, v122, v123
	v_cvt_pk_bf16_f32 v120, v124, v125
	v_cvt_pk_bf16_f32 v121, v126, v127
	v_cvt_pk_bf16_f32 v122, v128, v129
	v_cvt_pk_bf16_f32 v123, v130, v131
	global_store_dwordx2 v237, v[116:117], s[34:35] offset:0
	global_store_dwordx2 v237, v[118:119], s[34:35] offset:512
	global_store_dwordx2 v237, v[120:121], s[34:35] offset:1024
	global_store_dwordx2 v237, v[122:123], s[34:35] offset:1536
	s_cmp_lt_u32 s6, s7
	s_cbranch_scc0 .Lrp00_done
	s_sub_u32 s9, s6, 0x2000
	s_ashr_i32 s9, s9, 10
	s_add_i32 s9, s9, 1
	s_max_i32 s9, s9, 0
	s_cmp_eq_u32 s9, s8
	s_cbranch_scc1 .Lrp00_same1
	s_mov_b32 s8, s9
	s_add_i32 s9, s8, 0
	s_mul_i32 s9, s9, 0x6000
	s_add_u32 s36, s22, s9
	s_addc_u32 s37, s23, 0
	global_load_dwordx4 v[68:71], v236, s[12:13] offset:0
	global_load_dwordx4 v[72:75], v236, s[12:13] offset:1024
	global_load_dwordx4 v[76:79], v236, s[12:13] offset:2048
	global_load_dwordx4 v[100:103], v236, s[12:13] offset:3072
	s_add_u32 s38, s36, 0x1000
	s_addc_u32 s39, s37, 0
	global_load_dwordx4 v[104:107], v236, s[38:39] offset:0
	global_load_dwordx4 v[108:111], v236, s[38:39] offset:1024
	global_load_dwordx4 v[112:115], v236, s[38:39] offset:2048
	global_load_dwordx4 v[116:119], v236, s[38:39] offset:3072
	s_add_u32 s38, s36, 0x0
	s_addc_u32 s39, s37, 0
	global_load_dwordx4 v[172:175], v236, s[38:39] offset:0
	global_load_dwordx4 v[176:179], v236, s[38:39] offset:1024
	global_load_dwordx4 v[180:183], v236, s[38:39] offset:2048
	global_load_dwordx4 v[184:187], v236, s[38:39] offset:3072
	s_waitcnt vmcnt(0)
	v_add_f32_e32 v104, 1.0, v104
	v_add_f32_e32 v105, 1.0, v105
	v_add_f32_e32 v106, 1.0, v106
	v_add_f32_e32 v107, 1.0, v107
	v_add_f32_e32 v108, 1.0, v108
	v_add_f32_e32 v109, 1.0, v109
	v_add_f32_e32 v110, 1.0, v110
	v_add_f32_e32 v111, 1.0, v111
	v_add_f32_e32 v112, 1.0, v112
	v_add_f32_e32 v113, 1.0, v113
	v_add_f32_e32 v114, 1.0, v114
	v_add_f32_e32 v115, 1.0, v115
	v_add_f32_e32 v116, 1.0, v116
	v_add_f32_e32 v117, 1.0, v117
	v_add_f32_e32 v118, 1.0, v118
	v_add_f32_e32 v119, 1.0, v119
	v_mul_f32_e32 v156, v68, v104
	v_mul_f32_e32 v157, v69, v105
	v_mul_f32_e32 v158, v70, v106
	v_mul_f32_e32 v159, v71, v107
	v_mul_f32_e32 v160, v72, v108
	v_mul_f32_e32 v161, v73, v109
	v_mul_f32_e32 v162, v74, v110
	v_mul_f32_e32 v163, v75, v111
	v_mul_f32_e32 v164, v76, v112
	v_mul_f32_e32 v165, v77, v113
	v_mul_f32_e32 v166, v78, v114
	v_mul_f32_e32 v167, v79, v115
	v_mul_f32_e32 v168, v100, v116
	v_mul_f32_e32 v169, v101, v117
	v_mul_f32_e32 v170, v102, v118
	v_mul_f32_e32 v171, v103, v119
.Lrp00_same1:
	s_lshl_b32 s9, s6, 11
	s_add_u32 s9, s9, 0x30f8100
	s_add_u32 s34, s20, s9
	s_addc_u32 s35, s21, 0
	s_add_i32 s6, s6, 1
	s_cmp_lt_u32 s6, s7
	s_cbranch_scc0 .Lrp00_last1
	s_cmp_lt_u32 s6, 0x2000
	s_cselect_b32 s24, s16, s18
	s_cselect_b32 s25, s17, s19
	s_cselect_b32 s9, 0, 0x2000
	s_sub_u32 s9, s6, s9
	s_lshl_b32 s9, s9, 12
	s_add_u32 s24, s24, s9
	s_addc_u32 s25, s25, 0
	global_load_dwordx4 v[188:191], v236, s[24:25] offset:0
	global_load_dwordx4 v[192:195], v236, s[24:25] offset:1024
	global_load_dwordx4 v[196:199], v236, s[24:25] offset:2048
	global_load_dwordx4 v[200:203], v236, s[24:25] offset:3072
	s_waitcnt vmcnt(8)
	s_branch .Lrp00_go1

.Lrp00_go1:
	v_mul_f32_e32 v132, v212, v212
	v_mul_f32_e32 v133, v213, v213
	v_fmac_f32_e32 v132, v214, v214
	v_fmac_f32_e32 v133, v215, v215
	v_fmac_f32_e32 v132, v216, v216
	v_fmac_f32_e32 v133, v217, v217
	v_fmac_f32_e32 v132, v218, v218
	v_fmac_f32_e32 v133, v219, v219
	v_fmac_f32_e32 v132, v220, v220
	v_fmac_f32_e32 v133, v221, v221
	v_fmac_f32_e32 v132, v222, v222
	v_fmac_f32_e32 v133, v223, v223
	v_fmac_f32_e32 v132, v224, v224
	v_fmac_f32_e32 v133, v225, v225
	v_fmac_f32_e32 v132, v226, v226
	v_fmac_f32_e32 v133, v227, v227
	v_add_f32_e32 v132, v132, v133
	s_nop 1
	v_add_f32_dpp v132, v132, v132 quad_perm:[1,0,3,2] row_mask:0xf bank_mask:0xf bound_ctrl:1
	s_nop 1
	v_add_f32_dpp v132, v132, v132 quad_perm:[2,3,0,1] row_mask:0xf bank_mask:0xf bound_ctrl:1
	s_nop 1
	v_add_f32_dpp v132, v132, v132 row_ror:4 row_mask:0xf bank_mask:0xf bound_ctrl:1
	s_nop 1
	v_add_f32_dpp v132, v132, v132 row_ror:8 row_mask:0xf bank_mask:0xf bound_ctrl:1
	s_nop 1
	v_readlane_b32 s9, v132, 0
	v_readlane_b32 s38, v132, 16
	v_readlane_b32 s39, v132, 32
	v_readlane_b32 s40, v132, 48
	s_nop 2
	v_mov_b32_e32 v132, s9
	v_add_f32_e32 v132, s38, v132
	v_mov_b32_e32 v135, s39
	v_add_f32_e32 v135, s40, v135
	v_add_f32_e32 v132, v132, v135
	v_fmamk_f32 v132, v132, 0x3a800000, v238
	v_rsq_f32_e32 v132, v132
	s_nop 0
	v_mul_f32_e32 v116, v212, v132
	v_mul_f32_e32 v117, v213, v132
	v_mul_f32_e32 v118, v214, v132
	v_mul_f32_e32 v119, v215, v132
	v_mul_f32_e32 v120, v216, v132
	v_mul_f32_e32 v121, v217, v132
	v_mul_f32_e32 v122, v218, v132
	v_mul_f32_e32 v123, v219, v132
	v_mul_f32_e32 v124, v220, v132
	v_mul_f32_e32 v125, v221, v132
	v_mul_f32_e32 v126, v222, v132
	v_mul_f32_e32 v127, v223, v132
	v_mul_f32_e32 v128, v224, v132
	v_mul_f32_e32 v129, v225, v132
	v_mul_f32_e32 v130, v226, v132
	v_mul_f32_e32 v131, v227, v132
	v_fma_f32 v116, v116, v156, v172
	v_fma_f32 v117, v117, v157, v173
	v_fma_f32 v118, v118, v158, v174
	v_fma_f32 v119, v119, v159, v175
	v_fma_f32 v120, v120, v160, v176
	v_fma_f32 v121, v121, v161, v177
	v_fma_f32 v122, v122, v162, v178
	v_fma_f32 v123, v123, v163, v179
	v_fma_f32 v124, v124, v164, v180
	v_fma_f32 v125, v125, v165, v181
	v_fma_f32 v126, v126, v166, v182
	v_fma_f32 v127, v127, v167, v183
	v_fma_f32 v128, v128, v168, v184
	v_fma_f32 v129, v129, v169, v185
	v_fma_f32 v130, v130, v170, v186
	v_fma_f32 v131, v131, v171, v187
	v_cvt_pk_bf16_f32 v116, v116, v117
	v_cvt_pk_bf16_f32 v117, v118, v119
	v_cvt_pk_bf16_f32 v118, v120, v121
	v_cvt_pk_bf16_f32 v119, v122, v123
	v_cvt_pk_bf16_f32 v120, v124, v125
	v_cvt_pk_bf16_f32 v121, v126, v127
	v_cvt_pk_bf16_f32 v122, v128, v129
	v_cvt_pk_bf16_f32 v123, v130, v131
	global_store_dwordx2 v237, v[116:117], s[34:35] offset:0
	global_store_dwordx2 v237, v[118:119], s[34:35] offset:512
	global_store_dwordx2 v237, v[120:121], s[34:35] offset:1024
	global_store_dwordx2 v237, v[122:123], s[34:35] offset:1536
	s_cmp_lt_u32 s6, s7
	s_cbranch_scc1 .Lrp00_loop
.Lrp00_done:
.LBB0_218:
	s_or_b64 exec, exec, s[0:1]
	s_waitcnt vmcnt(0)
	s_barrier
	s_mov_b64 s[0:1], exec
	v_readlane_b32 s2, v242, 5
	v_readlane_b32 s3, v242, 6
	s_and_b64 s[2:3], s[0:1], s[2:3]
	s_xor_b64 s[0:1], s[2:3], s[0:1]
	s_mov_b64 exec, s[2:3]
	s_cbranch_execz .LBB0_271
	s_waitcnt vmcnt(0) lgkmcnt(0)
	v_mov_b32_e32 v0, 0x12008
	ds_read_b64 v[0:1], v0
	v_readlane_b32 s2, v242, 7
	v_readlane_b32 s3, v242, 8
	v_readlane_b32 s4, v242, 9
	v_mov_b32_e32 v2, 0
	v_mov_b32_e32 v3, 1
	s_lshl_b32 s4, s4, 8
	s_add_i32 s4, s4, 0x1400
	s_add_u32 s6, s2, s4
	s_addc_u32 s7, s3, 0
	s_add_u32 s8, s2, 0x3400
	s_addc_u32 s9, s3, 0
	s_add_i32 s10, s98, 1
	global_atomic_add v4, v2, v3, s[6:7] sc0
	s_waitcnt lgkmcnt(0)
	v_readfirstlane_b32 s11, v0
	v_readfirstlane_b32 s12, v1
	s_mul_i32 s13, s10, s11
	s_mul_i32 s12, s10, s12
	s_waitcnt vmcnt(0)
	v_readfirstlane_b32 s14, v4
	s_add_i32 s14, s14, 1
	s_cmp_lg_u32 s14, s13
	s_cbranch_scc1 .Lxb1_wait
	buffer_wbl2 sc1
	s_waitcnt vmcnt(0)
	global_atomic_add v2, v3, s[8:9]

.LBB0_1030:
	s_or_b64 exec, exec, s[0:1]
	s_waitcnt lgkmcnt(0)
	v_mov_b32_e32 v0, v137
	v_readlane_b32 s0, v242, 0
	s_barrier
	s_nop 0
	v_ashrrev_i32_e32 v1, 6, v0
	s_waitcnt vmcnt(7)
	v_lshl_add_u32 v4, s0, 2, v1
	s_movk_i32 s0, 0x2800
	v_cmp_gt_i32_e32 vcc, s0, v4
	s_and_saveexec_b64 s[0:1], vcc
	s_cbranch_execz .LBB0_1033
	s_waitcnt vmcnt(0) lgkmcnt(0)
	v_readfirstlane_b32 s2, v4
	v_readlane_b32 s4, v242, 42
	v_readlane_b32 s5, v242, 43
	v_readlane_b32 s6, v242, 3
	v_readlane_b32 s7, v242, 4
	s_load_dword s3, s[4:5], 0x0
	s_sub_u32 s20, s4, 0x118
	s_subb_u32 s21, s5, 0
	s_load_dwordx2 s[22:23], s[20:21], 0xe0
	s_load_dwordx2 s[24:25], s[20:21], 0xe8
	v_and_b32_e32 v11, 63, v137
	v_lshrrev_b32_e32 v9, 4, v11
	v_and_b32_e32 v11, 15, v11
	v_lshlrev_b32_e32 v11, 2, v11
	v_lshl_add_u32 v5, v9, 6, v11
	v_and_b32_e32 v10, 1, v9
	v_add_u32_e32 v10, 4, v10
	v_lshl_add_u32 v7, v10, 6, v11
	v_lshlrev_b32_e32 v6, 2, v5
	v_lshlrev_b32_e32 v8, 2, v7
	v_lshlrev_b32_e32 v5, 1, v5
	v_lshlrev_b32_e32 v7, 1, v7
	v_lshlrev_b32_e32 v9, 2, v9
	v_lshlrev_b32_e32 v10, 2, v10
	v_mov_b32_e32 v126, 0x3a27c5ac
	v_mov_b32_e32 v127, 0x3c800000
	s_add_u32 s8, s6, 0xddc8100
	s_addc_u32 s9, s7, 0
	s_add_u32 s10, s6, 0xe548100
	s_addc_u32 s11, s7, 0
	s_add_u32 s12, s6, 0xd5f8100
	s_addc_u32 s13, s7, 0
	s_add_u32 s14, s6, 0x5b78d00
	s_addc_u32 s15, s7, 0
	s_add_u32 s16, s6, 0xdd78100
	s_addc_u32 s17, s7, 0
	s_add_u32 s18, s6, 0x30f8600
	s_addc_u32 s19, s7, 0
	s_waitcnt lgkmcnt(0)
	s_lshl_b32 s3, s3, 2
	global_load_dwordx4 v[12:15], v6, s[22:23]
	global_load_dwordx4 v[16:19], v8, s[22:23]
	global_load_dwordx4 v[20:23], v6, s[24:25]
	global_load_dwordx4 v[24:27], v8, s[24:25]
	s_mul_i32 s4, s2, 0x300
	s_add_u32 s20, s8, s4
	s_addc_u32 s21, s9, 0
	s_add_u32 s22, s10, s4
	s_addc_u32 s23, s11, 0
	s_add_u32 s24, s12, s4
	s_addc_u32 s25, s13, 0
	s_mul_i32 s4, s2, 0x1600
	s_add_u32 s26, s14, s4
	s_addc_u32 s27, s15, 0
	s_lshl_b32 s4, s2, 5
	s_add_u32 s28, s16, s4
	s_addc_u32 s29, s17, 0
	global_load_dwordx2 v[28:29], v5, s[20:21]
	global_load_dwordx2 v[30:31], v5, s[22:23]
	global_load_dwordx2 v[32:33], v5, s[24:25]
	global_load_dwordx4 v[34:37], v6, s[26:27]
	global_load_dword v38, v9, s[28:29]
	global_load_dwordx2 v[40:41], v7, s[20:21]
	global_load_dwordx2 v[42:43], v7, s[22:23]
	global_load_dwordx2 v[44:45], v7, s[24:25]
	global_load_dwordx4 v[46:49], v8, s[26:27]
	global_load_dword v50, v10, s[28:29]
	s_waitcnt vmcnt(0)
.Lpo0_loop:
	s_lshl_b32 s4, s2, 11
	s_add_u32 s40, s18, s4
	s_addc_u32 s41, s19, 0
	s_add_i32 s2, s2, s3
	s_cmp_lt_u32 s2, 0x2800
	s_cbranch_scc0 .Lpo0_last0
	s_mul_i32 s4, s2, 0x300
	s_add_u32 s30, s8, s4
	s_addc_u32 s31, s9, 0
	s_add_u32 s32, s10, s4
	s_addc_u32 s33, s11, 0
	s_add_u32 s34, s12, s4
	s_addc_u32 s35, s13, 0
	s_mul_i32 s4, s2, 0x1600
	s_add_u32 s36, s14, s4
	s_addc_u32 s37, s15, 0
	s_lshl_b32 s4, s2, 5
	s_add_u32 s38, s16, s4
	s_addc_u32 s39, s17, 0
	global_load_dwordx2 v[76:77], v5, s[30:31]
	global_load_dwordx2 v[78:79], v5, s[32:33]
	global_load_dwordx2 v[80:81], v5, s[34:35]
	global_load_dwordx4 v[82:85], v6, s[36:37]
	global_load_dword v86, v9, s[38:39]
	global_load_dwordx2 v[88:89], v7, s[30:31]
	global_load_dwordx2 v[90:91], v7, s[32:33]
	global_load_dwordx2 v[92:93], v7, s[34:35]
	global_load_dwordx4 v[94:97], v8, s[36:37]
	global_load_dword v98, v10, s[38:39]
	s_waitcnt vmcnt(12)
	s_branch .Lpo0_go0
.Lpo0_last0:
	s_waitcnt vmcnt(2)
.Lpo0_go0:
	v_lshlrev_b32_e32 v100, 16, v28
	v_and_b32_e32 v101, 0xffff0000, v28
	v_lshlrev_b32_e32 v110, 16, v30
	v_and_b32_e32 v111, 0xffff0000, v30
	v_lshlrev_b32_e32 v102, 16, v29
	v_and_b32_e32 v103, 0xffff0000, v29
	v_lshlrev_b32_e32 v112, 16, v31
	v_and_b32_e32 v113, 0xffff0000, v31
	v_add_f32_e32 v100, v100, v110
	v_add_f32_e32 v101, v101, v111
	v_add_f32_e32 v102, v102, v112
	v_add_f32_e32 v103, v103, v113
	v_lshlrev_b32_e32 v104, 16, v40
	v_and_b32_e32 v105, 0xffff0000, v40
	v_lshlrev_b32_e32 v114, 16, v42
	v_and_b32_e32 v115, 0xffff0000, v42
	v_lshlrev_b32_e32 v106, 16, v41
	v_and_b32_e32 v107, 0xffff0000, v41
	v_lshlrev_b32_e32 v116, 16, v43
	v_and_b32_e32 v117, 0xffff0000, v43
	v_add_f32_e32 v104, v104, v114
	v_add_f32_e32 v105, v105, v115
	v_add_f32_e32 v106, v106, v116
	v_add_f32_e32 v107, v107, v117
	v_add_f32_e32 v108, v100, v101
	v_add_f32_e32 v110, v102, v103
	v_add_f32_e32 v109, v104, v105
	v_add_f32_e32 v114, v106, v107
	v_add_f32_e32 v108, v108, v110
	v_add_f32_e32 v109, v109, v114
	s_nop 0
	v_add_f32_dpp v108, v108, v108 quad_perm:[1,0,3,2] row_mask:0xf bank_mask:0xf bound_ctrl:1
	v_add_f32_dpp v109, v109, v109 quad_perm:[1,0,3,2] row_mask:0xf bank_mask:0xf bound_ctrl:1
	v_lshlrev_b32_e32 v118, 16, v32
	v_add_f32_dpp v108, v108, v108 quad_perm:[2,3,0,1] row_mask:0xf bank_mask:0xf bound_ctrl:1
	v_add_f32_dpp v109, v109, v109 quad_perm:[2,3,0,1] row_mask:0xf bank_mask:0xf bound_ctrl:1
	v_and_b32_e32 v119, 0xffff0000, v32
	v_add_f32_dpp v108, v108, v108 row_ror:4 row_mask:0xf bank_mask:0xf bound_ctrl:1
	v_add_f32_dpp v109, v109, v109 row_ror:4 row_mask:0xf bank_mask:0xf bound_ctrl:1
	v_lshlrev_b32_e32 v120, 16, v33
	v_add_f32_dpp v108, v108, v108 row_ror:8 row_mask:0xf bank_mask:0xf bound_ctrl:1
	v_add_f32_dpp v109, v109, v109 row_ror:8 row_mask:0xf bank_mask:0xf bound_ctrl:1
	v_and_b32_e32 v121, 0xffff0000, v33
	v_lshlrev_b32_e32 v122, 16, v44
	v_mul_f32_e32 v108, v108, v127
	v_mul_f32_e32 v109, v109, v127
	v_sub_f32_e32 v100, v100, v108
	v_sub_f32_e32 v101, v101, v108
	v_sub_f32_e32 v102, v102, v108
	v_sub_f32_e32 v103, v103, v108
	v_sub_f32_e32 v104, v104, v109
	v_sub_f32_e32 v105, v105, v109
	v_sub_f32_e32 v106, v106, v109
	v_sub_f32_e32 v107, v107, v109
	v_mul_f32_e32 v108, v100, v100
	v_mul_f32_e32 v109, v104, v104
	v_fmac_f32_e32 v108, v101, v101
	v_fmac_f32_e32 v109, v105, v105
	v_fmac_f32_e32 v108, v102, v102
	v_fmac_f32_e32 v109, v106, v106
	v_fmac_f32_e32 v108, v103, v103
	v_fmac_f32_e32 v109, v107, v107
	s_nop 0
	v_add_f32_dpp v108, v108, v108 quad_perm:[1,0,3,2] row_mask:0xf bank_mask:0xf bound_ctrl:1
	v_add_f32_dpp v109, v109, v109 quad_perm:[1,0,3,2] row_mask:0xf bank_mask:0xf bound_ctrl:1
	v_and_b32_e32 v123, 0xffff0000, v44
	v_add_f32_dpp v108, v108, v108 quad_perm:[2,3,0,1] row_mask:0xf bank_mask:0xf bound_ctrl:1
	v_add_f32_dpp v109, v109, v109 quad_perm:[2,3,0,1] row_mask:0xf bank_mask:0xf bound_ctrl:1
	v_lshlrev_b32_e32 v124, 16, v45
	v_add_f32_dpp v108, v108, v108 row_ror:4 row_mask:0xf bank_mask:0xf bound_ctrl:1
	v_add_f32_dpp v109, v109, v109 row_ror:4 row_mask:0xf bank_mask:0xf bound_ctrl:1
	v_and_b32_e32 v125, 0xffff0000, v45
	v_add_f32_dpp v108, v108, v108 row_ror:8 row_mask:0xf bank_mask:0xf bound_ctrl:1
	v_add_f32_dpp v109, v109, v109 row_ror:8 row_mask:0xf bank_mask:0xf bound_ctrl:1
	s_nop 0
	v_fma_f32 v108, v108, v127, v126
	v_fma_f32 v109, v109, v127, v126
	v_rsq_f32_e32 v108, v108
	v_rsq_f32_e32 v109, v109
	v_fma_f32 v110, v38, v34, v20
	v_fma_f32 v111, v38, v35, v21
	v_fma_f32 v112, v38, v36, v22
	v_fma_f32 v113, v38, v37, v23
	v_fma_f32 v114, v50, v46, v24
	v_fma_f32 v115, v50, v47, v25
	v_fma_f32 v116, v50, v48, v26
	v_fma_f32 v117, v50, v49, v27
	v_mul_f32_e32 v100, v100, v108
	v_mul_f32_e32 v101, v101, v108
	v_mul_f32_e32 v102, v102, v108
	v_mul_f32_e32 v103, v103, v108
	v_mul_f32_e32 v104, v104, v109
	v_mul_f32_e32 v105, v105, v109
	v_mul_f32_e32 v106, v106, v109
	v_mul_f32_e32 v107, v107, v109
	v_fmac_f32_e32 v110, v100, v12
	v_fmac_f32_e32 v111, v101, v13
	v_fmac_f32_e32 v112, v102, v14
	v_fmac_f32_e32 v113, v103, v15
	v_fmac_f32_e32 v114, v104, v16
	v_fmac_f32_e32 v115, v105, v17
	v_fmac_f32_e32 v116, v106, v18
	v_fmac_f32_e32 v117, v107, v19
	v_mul_f32_e32 v110, v110, v118
	v_mul_f32_e32 v111, v111, v119
	v_mul_f32_e32 v112, v112, v120
	v_mul_f32_e32 v113, v113, v121
	v_mul_f32_e32 v114, v114, v122
	v_mul_f32_e32 v115, v115, v123
	v_mul_f32_e32 v116, v116, v124
	v_mul_f32_e32 v117, v117, v125
	v_cvt_pk_bf16_f32 v110, v110, v111
	v_cvt_pk_bf16_f32 v111, v112, v113
	v_cvt_pk_bf16_f32 v114, v114, v115
	v_cvt_pk_bf16_f32 v115, v116, v117
	global_store_dwordx2 v5, v[110:111], s[40:41]
	global_store_dwordx2 v7, v[114:115], s[40:41]
	s_cmp_lt_u32 s2, 0x2800
	s_cbranch_scc0 .Lpo0_done
	s_lshl_b32 s4, s2, 11
	s_add_u32 s40, s18, s4
	s_addc_u32 s41, s19, 0
	s_add_i32 s2, s2, s3
	s_cmp_lt_u32 s2, 0x2800
	s_cbranch_scc0 .Lpo0_last1
	s_mul_i32 s4, s2, 0x300
	s_add_u32 s20, s8, s4
	s_addc_u32 s21, s9, 0
	s_add_u32 s22, s10, s4
	s_addc_u32 s23, s11, 0
	s_add_u32 s24, s12, s4
	s_addc_u32 s25, s13, 0
	s_mul_i32 s4, s2, 0x1600
	s_add_u32 s26, s14, s4
	s_addc_u32 s27, s15, 0
	s_lshl_b32 s4, s2, 5
	s_add_u32 s28, s16, s4
	s_addc_u32 s29, s17, 0
	global_load_dwordx2 v[28:29], v5, s[20:21]
	global_load_dwordx2 v[30:31], v5, s[22:23]
	global_load_dwordx2 v[32:33], v5, s[24:25]
	global_load_dwordx4 v[34:37], v6, s[26:27]
	global_load_dword v38, v9, s[28:29]
	global_load_dwordx2 v[40:41], v7, s[20:21]
	global_load_dwordx2 v[42:43], v7, s[22:23]
	global_load_dwordx2 v[44:45], v7, s[24:25]
	global_load_dwordx4 v[46:49], v8, s[26:27]
	global_load_dword v50, v10, s[28:29]
	s_waitcnt vmcnt(12)
	s_branch .Lpo0_go1

.Lpo0_go1:
	v_lshlrev_b32_e32 v100, 16, v76
	v_and_b32_e32 v101, 0xffff0000, v76
	v_lshlrev_b32_e32 v110, 16, v78
	v_and_b32_e32 v111, 0xffff0000, v78
	v_lshlrev_b32_e32 v102, 16, v77
	v_and_b32_e32 v103, 0xffff0000, v77
	v_lshlrev_b32_e32 v112, 16, v79
	v_and_b32_e32 v113, 0xffff0000, v79
	v_add_f32_e32 v100, v100, v110
	v_add_f32_e32 v101, v101, v111
	v_add_f32_e32 v102, v102, v112
	v_add_f32_e32 v103, v103, v113
	v_lshlrev_b32_e32 v104, 16, v88
	v_and_b32_e32 v105, 0xffff0000, v88
	v_lshlrev_b32_e32 v114, 16, v90
	v_and_b32_e32 v115, 0xffff0000, v90
	v_lshlrev_b32_e32 v106, 16, v89
	v_and_b32_e32 v107, 0xffff0000, v89
	v_lshlrev_b32_e32 v116, 16, v91
	v_and_b32_e32 v117, 0xffff0000, v91
	v_add_f32_e32 v104, v104, v114
	v_add_f32_e32 v105, v105, v115
	v_add_f32_e32 v106, v106, v116
	v_add_f32_e32 v107, v107, v117
	v_add_f32_e32 v108, v100, v101
	v_add_f32_e32 v110, v102, v103
	v_add_f32_e32 v109, v104, v105
	v_add_f32_e32 v114, v106, v107
	v_add_f32_e32 v108, v108, v110
	v_add_f32_e32 v109, v109, v114
	s_nop 0
	v_add_f32_dpp v108, v108, v108 quad_perm:[1,0,3,2] row_mask:0xf bank_mask:0xf bound_ctrl:1
	v_add_f32_dpp v109, v109, v109 quad_perm:[1,0,3,2] row_mask:0xf bank_mask:0xf bound_ctrl:1
	v_lshlrev_b32_e32 v118, 16, v80
	v_add_f32_dpp v108, v108, v108 quad_perm:[2,3,0,1] row_mask:0xf bank_mask:0xf bound_ctrl:1
	v_add_f32_dpp v109, v109, v109 quad_perm:[2,3,0,1] row_mask:0xf bank_mask:0xf bound_ctrl:1
	v_and_b32_e32 v119, 0xffff0000, v80
	v_add_f32_dpp v108, v108, v108 row_ror:4 row_mask:0xf bank_mask:0xf bound_ctrl:1
	v_add_f32_dpp v109, v109, v109 row_ror:4 row_mask:0xf bank_mask:0xf bound_ctrl:1
	v_lshlrev_b32_e32 v120, 16, v81
	v_add_f32_dpp v108, v108, v108 row_ror:8 row_mask:0xf bank_mask:0xf bound_ctrl:1
	v_add_f32_dpp v109, v109, v109 row_ror:8 row_mask:0xf bank_mask:0xf bound_ctrl:1
	v_and_b32_e32 v121, 0xffff0000, v81
	v_lshlrev_b32_e32 v122, 16, v92
	v_mul_f32_e32 v108, v108, v127
	v_mul_f32_e32 v109, v109, v127
	v_sub_f32_e32 v100, v100, v108
	v_sub_f32_e32 v101, v101, v108
	v_sub_f32_e32 v102, v102, v108
	v_sub_f32_e32 v103, v103, v108
	v_sub_f32_e32 v104, v104, v109
	v_sub_f32_e32 v105, v105, v109
	v_sub_f32_e32 v106, v106, v109
	v_sub_f32_e32 v107, v107, v109
	v_mul_f32_e32 v108, v100, v100
	v_mul_f32_e32 v109, v104, v104
	v_fmac_f32_e32 v108, v101, v101
	v_fmac_f32_e32 v109, v105, v105
	v_fmac_f32_e32 v108, v102, v102
	v_fmac_f32_e32 v109, v106, v106
	v_fmac_f32_e32 v108, v103, v103
	v_fmac_f32_e32 v109, v107, v107
	s_nop 0
	v_add_f32_dpp v108, v108, v108 quad_perm:[1,0,3,2] row_mask:0xf bank_mask:0xf bound_ctrl:1
	v_add_f32_dpp v109, v109, v109 quad_perm:[1,0,3,2] row_mask:0xf bank_mask:0xf bound_ctrl:1
	v_and_b32_e32 v123, 0xffff0000, v92
	v_add_f32_dpp v108, v108, v108 quad_perm:[2,3,0,1] row_mask:0xf bank_mask:0xf bound_ctrl:1
	v_add_f32_dpp v109, v109, v109 quad_perm:[2,3,0,1] row_mask:0xf bank_mask:0xf bound_ctrl:1
	v_lshlrev_b32_e32 v124, 16, v93
	v_add_f32_dpp v108, v108, v108 row_ror:4 row_mask:0xf bank_mask:0xf bound_ctrl:1
	v_add_f32_dpp v109, v109, v109 row_ror:4 row_mask:0xf bank_mask:0xf bound_ctrl:1
	v_and_b32_e32 v125, 0xffff0000, v93
	v_add_f32_dpp v108, v108, v108 row_ror:8 row_mask:0xf bank_mask:0xf bound_ctrl:1
	v_add_f32_dpp v109, v109, v109 row_ror:8 row_mask:0xf bank_mask:0xf bound_ctrl:1
	s_nop 0
	v_fma_f32 v108, v108, v127, v126
	v_fma_f32 v109, v109, v127, v126
	v_rsq_f32_e32 v108, v108
	v_rsq_f32_e32 v109, v109
	v_fma_f32 v110, v86, v82, v20
	v_fma_f32 v111, v86, v83, v21
	v_fma_f32 v112, v86, v84, v22
	v_fma_f32 v113, v86, v85, v23
	v_fma_f32 v114, v98, v94, v24
	v_fma_f32 v115, v98, v95, v25
	v_fma_f32 v116, v98, v96, v26
	v_fma_f32 v117, v98, v97, v27
	v_mul_f32_e32 v100, v100, v108
	v_mul_f32_e32 v101, v101, v108
	v_mul_f32_e32 v102, v102, v108
	v_mul_f32_e32 v103, v103, v108
	v_mul_f32_e32 v104, v104, v109
	v_mul_f32_e32 v105, v105, v109
	v_mul_f32_e32 v106, v106, v109
	v_mul_f32_e32 v107, v107, v109
	v_fmac_f32_e32 v110, v100, v12
	v_fmac_f32_e32 v111, v101, v13
	v_fmac_f32_e32 v112, v102, v14
	v_fmac_f32_e32 v113, v103, v15
	v_fmac_f32_e32 v114, v104, v16
	v_fmac_f32_e32 v115, v105, v17
	v_fmac_f32_e32 v116, v106, v18
	v_fmac_f32_e32 v117, v107, v19
	v_mul_f32_e32 v110, v110, v118
	v_mul_f32_e32 v111, v111, v119
	v_mul_f32_e32 v112, v112, v120
	v_mul_f32_e32 v113, v113, v121
	v_mul_f32_e32 v114, v114, v122
	v_mul_f32_e32 v115, v115, v123
	v_mul_f32_e32 v116, v116, v124
	v_mul_f32_e32 v117, v117, v125
	v_cvt_pk_bf16_f32 v110, v110, v111
	v_cvt_pk_bf16_f32 v111, v112, v113
	v_cvt_pk_bf16_f32 v114, v114, v115
	v_cvt_pk_bf16_f32 v115, v116, v117
	global_store_dwordx2 v5, v[110:111], s[40:41]
	global_store_dwordx2 v7, v[114:115], s[40:41]
	s_cmp_lt_u32 s2, 0x2800
	s_cbranch_scc1 .Lpo0_loop
.Lpo0_done:
.LBB0_1033:
	s_or_b64 exec, exec, s[0:1]
	s_waitcnt vmcnt(0)
	s_barrier
	s_mov_b64 s[0:1], exec
	v_readlane_b32 s2, v242, 5
	v_readlane_b32 s3, v242, 6
	s_and_b64 s[2:3], s[0:1], s[2:3]
	v_readlane_b32 s41, v241, 14
	s_mov_b64 exec, s[2:3]
	s_cbranch_execz .LBB0_1085
	s_waitcnt vmcnt(0) lgkmcnt(0)
	v_mov_b32_e32 v0, 0x12008
	ds_read_b64 v[0:1], v0
	v_readlane_b32 s2, v242, 7
	v_readlane_b32 s3, v242, 8
	v_readlane_b32 s4, v242, 9
	v_mov_b32_e32 v2, 0
	v_mov_b32_e32 v3, 1
	s_lshl_b32 s4, s4, 8
	s_add_i32 s4, s4, 0x1400
	s_add_u32 s6, s2, s4
	s_addc_u32 s7, s3, 0
	s_add_u32 s8, s2, 0x3400
	s_addc_u32 s9, s3, 0
	s_add_i32 s10, s98, 1
	global_atomic_add v4, v2, v3, s[6:7] sc0
	s_waitcnt lgkmcnt(0)
	v_readfirstlane_b32 s11, v0
	v_readfirstlane_b32 s12, v1
	s_mul_i32 s13, s10, s11
	s_mul_i32 s12, s10, s12
	s_waitcnt vmcnt(0)
	v_readfirstlane_b32 s14, v4
	s_add_i32 s14, s14, 1
	s_cmp_lg_u32 s14, s13
	s_cbranch_scc1 .Lxb5_wait
	buffer_wbl2 sc1
	s_waitcnt vmcnt(0)
	global_atomic_add v2, v3, s[8:9]

.LBB0_2028:
	s_or_b64 exec, exec, s[0:1]
	s_waitcnt lgkmcnt(0)
	v_mov_b32_e32 v0, v137
	v_readlane_b32 s0, v242, 0
	s_barrier
	s_nop 0
	v_ashrrev_i32_e32 v1, 6, v0
	s_waitcnt vmcnt(7)
	v_lshl_add_u32 v4, s0, 2, v1
	s_movk_i32 s0, 0x2800
	v_cmp_gt_i32_e32 vcc, s0, v4
	s_and_saveexec_b64 s[0:1], vcc
	s_cbranch_execz .LBB0_2031
	s_waitcnt vmcnt(0) lgkmcnt(0)
	v_readfirstlane_b32 s2, v4
	v_readlane_b32 s4, v242, 42
	v_readlane_b32 s5, v242, 43
	v_readlane_b32 s6, v242, 3
	v_readlane_b32 s7, v242, 4
	s_load_dword s3, s[4:5], 0x0
	s_sub_u32 s20, s4, 0x118
	s_subb_u32 s21, s5, 0
	s_load_dwordx2 s[22:23], s[20:21], 0xe0
	s_load_dwordx2 s[24:25], s[20:21], 0xe8
	v_and_b32_e32 v11, 63, v137
	v_lshrrev_b32_e32 v9, 4, v11
	v_and_b32_e32 v11, 15, v11
	v_lshlrev_b32_e32 v11, 2, v11
	v_lshl_add_u32 v5, v9, 6, v11
	v_and_b32_e32 v10, 1, v9
	v_add_u32_e32 v10, 4, v10
	v_lshl_add_u32 v7, v10, 6, v11
	v_lshlrev_b32_e32 v6, 2, v5
	v_lshlrev_b32_e32 v8, 2, v7
	v_lshlrev_b32_e32 v5, 1, v5
	v_lshlrev_b32_e32 v7, 1, v7
	v_lshlrev_b32_e32 v9, 2, v9
	v_lshlrev_b32_e32 v10, 2, v10
	v_mov_b32_e32 v126, 0x3a27c5ac
	v_mov_b32_e32 v127, 0x3c800000
	s_add_u32 s8, s6, 0xddc8100
	s_addc_u32 s9, s7, 0
	s_add_u32 s10, s6, 0xe548100
	s_addc_u32 s11, s7, 0
	s_add_u32 s12, s6, 0xd5f8100
	s_addc_u32 s13, s7, 0
	s_add_u32 s14, s6, 0x5b78d00
	s_addc_u32 s15, s7, 0
	s_add_u32 s16, s6, 0xdd78100
	s_addc_u32 s17, s7, 0
	s_add_u32 s18, s6, 0x30f8600
	s_addc_u32 s19, s7, 0
	s_waitcnt lgkmcnt(0)
	s_lshl_b32 s3, s3, 2
	s_add_u32 s22, s22, 0x600
	s_addc_u32 s23, s23, 0
	s_add_u32 s24, s24, 0x600
	s_addc_u32 s25, s25, 0
	global_load_dwordx4 v[12:15], v6, s[22:23]
	global_load_dwordx4 v[16:19], v8, s[22:23]
	global_load_dwordx4 v[20:23], v6, s[24:25]
	global_load_dwordx4 v[24:27], v8, s[24:25]
	s_mul_i32 s4, s2, 0x300
	s_add_u32 s20, s8, s4
	s_addc_u32 s21, s9, 0
	s_add_u32 s22, s10, s4
	s_addc_u32 s23, s11, 0
	s_add_u32 s24, s12, s4
	s_addc_u32 s25, s13, 0
	s_mul_i32 s4, s2, 0x1600
	s_add_u32 s26, s14, s4
	s_addc_u32 s27, s15, 0
	s_lshl_b32 s4, s2, 5
	s_add_u32 s28, s16, s4
	s_addc_u32 s29, s17, 0
	global_load_dwordx2 v[28:29], v5, s[20:21]
	global_load_dwordx2 v[30:31], v5, s[22:23]
	global_load_dwordx2 v[32:33], v5, s[24:25]
	global_load_dwordx4 v[34:37], v6, s[26:27]
	global_load_dword v38, v9, s[28:29]
	global_load_dwordx2 v[40:41], v7, s[20:21]
	global_load_dwordx2 v[42:43], v7, s[22:23]
	global_load_dwordx2 v[44:45], v7, s[24:25]
	global_load_dwordx4 v[46:49], v8, s[26:27]
	global_load_dword v50, v10, s[28:29]
	s_waitcnt vmcnt(0)

.Lpo1_done:
.LBB0_2031:
	s_or_b64 exec, exec, s[0:1]
	s_waitcnt vmcnt(0)
	s_barrier
	s_mov_b64 s[0:1], exec
	v_readlane_b32 s2, v242, 5
	v_readlane_b32 s3, v242, 6
	v_readlane_b32 s44, v241, 45
	s_and_b64 s[2:3], s[0:1], s[2:3]
	v_readlane_b32 s45, v241, 46
	v_readlane_b32 s56, v242, 56
	v_readlane_b32 s57, v242, 54
	s_mov_b64 exec, s[2:3]
	s_cbranch_execz .LBB0_2083
	s_waitcnt vmcnt(0) lgkmcnt(0)
	v_mov_b32_e32 v0, 0x12008
	ds_read_b64 v[0:1], v0
	v_readlane_b32 s2, v242, 7
	v_readlane_b32 s3, v242, 8
	v_readlane_b32 s4, v242, 9
	v_mov_b32_e32 v2, 0
	v_mov_b32_e32 v3, 1
	s_lshl_b32 s4, s4, 8
	s_add_i32 s4, s4, 0x1400
	s_add_u32 s6, s2, s4
	s_addc_u32 s7, s3, 0
	s_add_u32 s8, s2, 0x3400
	s_addc_u32 s9, s3, 0
	s_add_i32 s10, s98, 1
	global_atomic_add v4, v2, v3, s[6:7] sc0
	s_waitcnt lgkmcnt(0)
	v_readfirstlane_b32 s11, v0
	v_readfirstlane_b32 s12, v1
	s_mul_i32 s13, s10, s11
	s_mul_i32 s12, s10, s12
	s_waitcnt vmcnt(0)
	v_readfirstlane_b32 s14, v4
	s_add_i32 s14, s14, 1
	s_cmp_lg_u32 s14, s13
	s_cbranch_scc1 .Lxb14_wait
	buffer_wbl2 sc1
	s_waitcnt vmcnt(0)
	global_atomic_add v2, v3, s[8:9]
